# plus: conv LayerNorm in-row sums by fused DPP adds instead of LDS bpermute round trips
# baseline (speedup 1.0000x reference)
; DEVI uint32_t pk(float a, float b) { const hwf32x2 v = {a, b}; return __builtin_bit_cast(uint32_t, __builtin_convertvector(v, hwbf16x2)); }
; DEVI float fast_sigmoid(float x) { return __builtin_amdgcn_rcpf(1.f + __expf(-x)); }
; DEVI float wsum16(float v) {
;   v += __shfl_xor(v, 1); v += __shfl_xor(v, 2); v += __shfl_xor(v, 4); v += __shfl_xor(v, 8); return v;
; }
; DEVI float wsum64(float v) { v = wsum16(v); v += __shfl_xor(v, 16); v += __shfl_xor(v, 32); return v; }
; __device__ void phase_conv(const P& p, int vb, int nvb, char* smem) {
;     ...
; #pragma unroll 2
;     for (int q = 0; q < CT / 4; q++) {
;       const int tk = wave * (CT / 4) + q;
;       float v[8];
;       const float4 x0 = *(const float4*)(cv + tk * 512 + lane * 8), x1 = *(const float4*)(cv + tk * 512 + lane * 8 + 4);
;       v[0] = x0.x; v[1] = x0.y; v[2] = x0.z; v[3] = x0.w; v[4] = x1.x; v[5] = x1.y; v[6] = x1.z; v[7] = x1.w;
;       float s = 0.f;
; #pragma unroll
;       for (int e = 0; e < 8; e++) s += v[e];
;       const float mu = wsum64(s) * (1.f / 512.f);
;       float s2 = 0.f;
; #pragma unroll
;       for (int e = 0; e < 8; e++) { v[e] -= mu; s2 += v[e] * v[e]; }
;       const float rstd = rsqrtf(wsum64(s2) * (1.f / 512.f) + EPS);
;       float s3 = 0.f;
; #pragma unroll
;       for (int e = 0; e < 8; e++) {
;         const float y = v[e] * rstd * gln[e] + bln[e];
;         const float sl = y * fast_sigmoid(y);
;         v[e] = sl; s3 += sl * sl;
;       }
;       const float r2 = rsqrtf(wsum64(s3) * (1.f / 512.f) + EPS);
;       uint4 o = make_uint4(pk(v[0] * r2, v[1] * r2), pk(v[2] * r2, v[3] * r2), pk(v[4] * r2, v[5] * r2), pk(v[6] * r2, v[7] * r2));
;       *(uint4*)(mixed + (size_t)(b * TP + t0 + tk) * 1024 + 512 + lane * 8) = o;
;     }
.LBB0_137:
	ds_read_b128 v[16:19], v33
	ds_read_b128 v[34:37], v33 offset:16
	v_add_u32_e32 v46, s34, v32
	s_mov_b32 s35, 0x2864000
	s_add_i32 s34, s34, 2
	s_waitcnt lgkmcnt(1)
	v_add_f32_e32 v38, 0, v16
	v_add_f32_e32 v38, v38, v17
	v_add_f32_e32 v38, v38, v18
	v_add_f32_e32 v38, v38, v19
	s_waitcnt lgkmcnt(0)
	v_add_f32_e32 v38, v38, v34
	v_add_f32_e32 v38, v38, v35
	v_add_f32_e32 v38, v38, v36
	v_add_f32_e32 v38, v38, v37
	s_nop 1
	v_add_f32_dpp v38, v38, v38 quad_perm:[1,0,3,2] row_mask:0xf bank_mask:0xf
	s_cmp_eq_u32 s34, 0
	s_waitcnt lgkmcnt(0)
	s_nop 0
	s_nop 1
	v_add_f32_dpp v38, v38, v38 quad_perm:[2,3,0,1] row_mask:0xf bank_mask:0xf
	s_waitcnt lgkmcnt(0)
	s_nop 0
	s_nop 1
	v_add_f32_dpp v38, v38, v38 row_ror:4 row_mask:0xf bank_mask:0xf
	s_waitcnt lgkmcnt(0)
	s_nop 0
	s_nop 1
	v_add_f32_dpp v38, v38, v38 row_ror:8 row_mask:0xf bank_mask:0xf
	s_waitcnt lgkmcnt(0)
	s_nop 0
	ds_bpermute_b32 v39, v128, v38
	s_waitcnt lgkmcnt(0)
	v_add_f32_e32 v38, v38, v39
	ds_bpermute_b32 v39, v129, v38
	s_waitcnt lgkmcnt(0)
	v_add_f32_e32 v38, v38, v39
	v_mul_f32_e32 v38, 0x3b000000, v38
	v_pk_add_f32 v[16:17], v[16:17], v[38:39] op_sel_hi:[1,0] neg_lo:[0,1] neg_hi:[0,1]
	v_pk_add_f32 v[18:19], v[18:19], v[38:39] op_sel_hi:[1,0] neg_lo:[0,1] neg_hi:[0,1]
	v_pk_mul_f32 v[40:41], v[16:17], v[16:17]
	v_pk_mul_f32 v[42:43], v[18:19], v[18:19]
	v_add_f32_e32 v40, v40, v41
	v_pk_add_f32 v[34:35], v[34:35], v[38:39] op_sel_hi:[1,0] neg_lo:[0,1] neg_hi:[0,1]
	v_add_f32_e32 v40, v42, v40
	v_pk_mul_f32 v[44:45], v[34:35], v[34:35]
	v_add_f32_e32 v40, v43, v40
	v_pk_add_f32 v[36:37], v[36:37], v[38:39] op_sel_hi:[1,0] neg_lo:[0,1] neg_hi:[0,1]
	v_add_f32_e32 v40, v44, v40
	v_pk_mul_f32 v[38:39], v[36:37], v[36:37]
	v_add_f32_e32 v40, v45, v40
	v_add_f32_e32 v38, v38, v40
	v_add_f32_e32 v38, v39, v38
	s_nop 1
	v_add_f32_dpp v38, v38, v38 quad_perm:[1,0,3,2] row_mask:0xf bank_mask:0xf
	s_waitcnt lgkmcnt(0)
	s_nop 0
	s_nop 1
	v_add_f32_dpp v38, v38, v38 quad_perm:[2,3,0,1] row_mask:0xf bank_mask:0xf
	s_waitcnt lgkmcnt(0)
	s_nop 0
	s_nop 1
	v_add_f32_dpp v38, v38, v38 row_ror:4 row_mask:0xf bank_mask:0xf
	s_waitcnt lgkmcnt(0)
	s_nop 0
	s_nop 1
	v_add_f32_dpp v38, v38, v38 row_ror:8 row_mask:0xf bank_mask:0xf
	s_waitcnt lgkmcnt(0)
	s_nop 0
	ds_bpermute_b32 v39, v128, v38
	s_waitcnt lgkmcnt(0)
	v_add_f32_e32 v38, v38, v39
	ds_bpermute_b32 v39, v129, v38
	s_waitcnt lgkmcnt(0)
	v_add_f32_e32 v38, v38, v39
	v_fmamk_f32 v38, v38, 0x3b000000, v130
	v_cmp_gt_f32_e32 vcc, s26, v38
	v_mul_f32_e32 v39, 0x4b800000, v38
	s_nop 0
	v_cndmask_b32_e32 v38, v38, v39, vcc
	v_rsq_f32_e32 v38, v38
	s_nop 0
	v_mul_f32_e32 v39, 0x45800000, v38
	v_cndmask_b32_e32 v38, v38, v39, vcc
	v_pk_mul_f32 v[16:17], v[16:17], v[38:39] op_sel_hi:[1,0]
	s_nop 0
	v_pk_fma_f32 v[16:17], v[4:5], v[16:17], v[12:13]
	s_nop 0
	v_mul_f32_e32 v39, 0xbfb8aa3b, v16
	v_exp_f32_e32 v39, v39
	s_nop 0
	v_add_f32_e32 v39, 1.0, v39
	v_rcp_f32_e32 v40, v39
	v_mul_f32_e32 v39, 0xbfb8aa3b, v17
	v_exp_f32_e32 v39, v39
	s_nop 0
	v_add_f32_e32 v39, 1.0, v39
	v_pk_mul_f32 v[18:19], v[18:19], v[38:39] op_sel_hi:[1,0]
	v_rcp_f32_e32 v41, v39
	v_pk_fma_f32 v[18:19], v[6:7], v[18:19], v[14:15]
	v_pk_mul_f32 v[16:17], v[16:17], v[40:41]
	v_mul_f32_e32 v39, 0xbfb8aa3b, v18
	v_exp_f32_e32 v39, v39
	v_pk_mul_f32 v[40:41], v[16:17], v[16:17]
	v_add_f32_e32 v39, 1.0, v39
	v_rcp_f32_e32 v42, v39
	v_mul_f32_e32 v39, 0xbfb8aa3b, v19
	v_exp_f32_e32 v39, v39
	v_add_f32_e32 v40, v40, v41
	v_add_f32_e32 v39, 1.0, v39
	v_pk_mul_f32 v[34:35], v[34:35], v[38:39] op_sel_hi:[1,0]
	v_rcp_f32_e32 v43, v39
	v_pk_fma_f32 v[34:35], v[0:1], v[34:35], v[8:9]
	v_pk_mul_f32 v[18:19], v[18:19], v[42:43]
	v_mul_f32_e32 v39, 0xbfb8aa3b, v34
	v_exp_f32_e32 v39, v39
	v_pk_mul_f32 v[42:43], v[18:19], v[18:19]
	v_add_f32_e32 v39, 1.0, v39
	v_rcp_f32_e32 v44, v39
	v_mul_f32_e32 v39, 0xbfb8aa3b, v35
	v_exp_f32_e32 v39, v39
	v_add_f32_e32 v40, v42, v40
	v_add_f32_e32 v40, v43, v40
	v_add_f32_e32 v39, 1.0, v39
	v_pk_mul_f32 v[36:37], v[36:37], v[38:39] op_sel_hi:[1,0]
	v_rcp_f32_e32 v45, v39
	v_pk_fma_f32 v[36:37], v[2:3], v[36:37], v[10:11]
	v_pk_mul_f32 v[34:35], v[34:35], v[44:45]
	v_mul_f32_e32 v38, 0xbfb8aa3b, v36
	v_mul_f32_e32 v39, 0xbfb8aa3b, v37
	v_exp_f32_e32 v38, v38
	v_exp_f32_e32 v39, v39
	v_pk_mul_f32 v[44:45], v[34:35], v[34:35]
	v_add_f32_e32 v38, 1.0, v38
	v_add_f32_e32 v39, 1.0, v39
	v_rcp_f32_e32 v38, v38
	v_rcp_f32_e32 v39, v39
	v_add_f32_e32 v40, v44, v40
	v_add_f32_e32 v40, v45, v40
	v_pk_mul_f32 v[36:37], v[36:37], v[38:39]
	s_nop 0
	v_pk_mul_f32 v[38:39], v[36:37], v[36:37]
	s_nop 0
	v_add_f32_e32 v38, v38, v40
	v_add_f32_e32 v38, v39, v38
	s_nop 1
	v_add_f32_dpp v38, v38, v38 quad_perm:[1,0,3,2] row_mask:0xf bank_mask:0xf
	s_waitcnt lgkmcnt(0)
	s_nop 0
	s_nop 1
	v_add_f32_dpp v38, v38, v38 quad_perm:[2,3,0,1] row_mask:0xf bank_mask:0xf
	s_waitcnt lgkmcnt(0)
	s_nop 0
	s_nop 1
	v_add_f32_dpp v38, v38, v38 row_ror:4 row_mask:0xf bank_mask:0xf
	s_waitcnt lgkmcnt(0)
	s_nop 0
	s_nop 1
	v_add_f32_dpp v38, v38, v38 row_ror:8 row_mask:0xf bank_mask:0xf
	s_waitcnt lgkmcnt(0)
	s_nop 0
	ds_bpermute_b32 v39, v128, v38
	s_waitcnt lgkmcnt(0)
	v_add_f32_e32 v38, v38, v39
	ds_bpermute_b32 v39, v129, v38
	s_waitcnt lgkmcnt(0)
; DEVI uint32_t pk(float a, float b) { const hwf32x2 v = {a, b}; return __builtin_bit_cast(uint32_t, __builtin_convertvector(v, hwbf16x2)); }
; DEVI float fast_sigmoid(float x) { return __builtin_amdgcn_rcpf(1.f + __expf(-x)); }
; DEVI float wsum16(float v) {
;   v += __shfl_xor(v, 1); v += __shfl_xor(v, 2); v += __shfl_xor(v, 4); v += __shfl_xor(v, 8); return v;
; }
; DEVI float wsum64(float v) { v = wsum16(v); v += __shfl_xor(v, 16); v += __shfl_xor(v, 32); return v; }
; __device__ void phase_conv(const P& p, int vb, int nvb, char* smem) {
;     ...
; #pragma unroll 2
;     for (int q = 0; q < CT / 4; q++) {
;       const int tk = wave * (CT / 4) + q;
;       float v[8];
;       const float4 x0 = *(const float4*)(cv + tk * 512 + lane * 8), x1 = *(const float4*)(cv + tk * 512 + lane * 8 + 4);
;       v[0] = x0.x; v[1] = x0.y; v[2] = x0.z; v[3] = x0.w; v[4] = x1.x; v[5] = x1.y; v[6] = x1.z; v[7] = x1.w;
;       float s = 0.f;
; #pragma unroll
;       for (int e = 0; e < 8; e++) s += v[e];
;       const float mu = wsum64(s) * (1.f / 512.f);
;       float s2 = 0.f;
; #pragma unroll
;       for (int e = 0; e < 8; e++) { v[e] -= mu; s2 += v[e] * v[e]; }
;       const float rstd = rsqrtf(wsum64(s2) * (1.f / 512.f) + EPS);
;       float s3 = 0.f;
; #pragma unroll
;       for (int e = 0; e < 8; e++) {
;         const float y = v[e] * rstd * gln[e] + bln[e];
;         const float sl = y * fast_sigmoid(y);
;         v[e] = sl; s3 += sl * sl;
;       }
;       const float r2 = rsqrtf(wsum64(s3) * (1.f / 512.f) + EPS);
;       uint4 o = make_uint4(pk(v[0] * r2, v[1] * r2), pk(v[2] * r2, v[3] * r2), pk(v[4] * r2, v[5] * r2), pk(v[6] * r2, v[7] * r2));
;       *(uint4*)(mixed + (size_t)(b * TP + t0 + tk) * 1024 + 512 + lane * 8) = o;
;     }
	v_add_f32_e32 v38, v38, v39
	v_fmamk_f32 v38, v38, 0x3b000000, v130
	v_cmp_gt_f32_e32 vcc, s26, v38
	v_mul_f32_e32 v39, 0x4b800000, v38
	s_nop 0
	v_cndmask_b32_e32 v38, v38, v39, vcc
	v_rsq_f32_e32 v38, v38
	s_nop 0
	v_mul_f32_e32 v39, 0x45800000, v38
	v_cndmask_b32_e32 v38, v38, v39, vcc
	v_pk_mul_f32 v[16:17], v[16:17], v[38:39] op_sel_hi:[1,0]
	v_pk_mul_f32 v[18:19], v[18:19], v[38:39] op_sel_hi:[1,0]
	v_cvt_pk_bf16_f32 v16, v16, v17
	v_cvt_pk_bf16_f32 v17, v18, v19
	v_pk_mul_f32 v[18:19], v[34:35], v[38:39] op_sel_hi:[1,0]
	v_pk_mul_f32 v[34:35], v[36:37], v[38:39] op_sel_hi:[1,0]
	v_cvt_pk_bf16_f32 v18, v18, v19
	v_cvt_pk_bf16_f32 v19, v34, v35
	v_add_u32_e32 v34, 22, v46
	v_ashrrev_i32_e32 v35, 31, v34
	v_lshlrev_b64 v[34:35], 11, v[34:35]
	v_lshl_add_u64 v[34:35], s[80:81], 0, v[34:35]
	v_lshl_add_u64 v[34:35], v[34:35], 0, v[22:23]
	v_add_co_u32_e32 v34, vcc, s35, v34
	s_nop 1
	v_addc_co_u32_e32 v35, vcc, 0, v35, vcc
	global_store_dwordx4 v[34:35], v[16:19], off offset:1024
	ds_read_b128 v[16:19], v33 offset:2064
	ds_read_b128 v[34:37], v33 offset:2048
	v_add_u32_e32 v33, 0x1000, v33
	s_waitcnt lgkmcnt(0)
	v_add_f32_e32 v38, 0, v34
	v_add_f32_e32 v38, v38, v35
	v_add_f32_e32 v38, v38, v36
	v_add_f32_e32 v38, v38, v37
	v_add_f32_e32 v38, v38, v16
	v_add_f32_e32 v38, v38, v17
	v_add_f32_e32 v38, v38, v18
	v_add_f32_e32 v38, v38, v19
	s_nop 1
	v_add_f32_dpp v38, v38, v38 quad_perm:[1,0,3,2] row_mask:0xf bank_mask:0xf
	s_waitcnt lgkmcnt(0)
	s_nop 0
	s_nop 1
	v_add_f32_dpp v38, v38, v38 quad_perm:[2,3,0,1] row_mask:0xf bank_mask:0xf
	s_waitcnt lgkmcnt(0)
	s_nop 0
	s_nop 1
	v_add_f32_dpp v38, v38, v38 row_ror:4 row_mask:0xf bank_mask:0xf
	s_waitcnt lgkmcnt(0)
	s_nop 0
	s_nop 1
	v_add_f32_dpp v38, v38, v38 row_ror:8 row_mask:0xf bank_mask:0xf
	s_waitcnt lgkmcnt(0)
	s_nop 0
	ds_bpermute_b32 v39, v128, v38
	s_waitcnt lgkmcnt(0)
	v_add_f32_e32 v38, v38, v39
	ds_bpermute_b32 v39, v129, v38
	s_waitcnt lgkmcnt(0)
	v_add_f32_e32 v38, v38, v39
	v_mul_f32_e32 v38, 0x3b000000, v38
	v_pk_add_f32 v[34:35], v[34:35], v[38:39] op_sel_hi:[1,0] neg_lo:[0,1] neg_hi:[0,1]
	v_pk_add_f32 v[36:37], v[36:37], v[38:39] op_sel_hi:[1,0] neg_lo:[0,1] neg_hi:[0,1]
	v_pk_mul_f32 v[40:41], v[34:35], v[34:35]
	v_pk_mul_f32 v[42:43], v[36:37], v[36:37]
	v_add_f32_e32 v40, v40, v41
	v_pk_add_f32 v[16:17], v[16:17], v[38:39] op_sel_hi:[1,0] neg_lo:[0,1] neg_hi:[0,1]
	v_add_f32_e32 v40, v42, v40
	v_pk_mul_f32 v[44:45], v[16:17], v[16:17]
	v_add_f32_e32 v40, v43, v40
	v_pk_add_f32 v[18:19], v[18:19], v[38:39] op_sel_hi:[1,0] neg_lo:[0,1] neg_hi:[0,1]
	v_add_f32_e32 v40, v44, v40
	v_pk_mul_f32 v[38:39], v[18:19], v[18:19]
	v_add_f32_e32 v40, v45, v40
	v_add_f32_e32 v38, v38, v40
	v_add_f32_e32 v38, v39, v38
	s_nop 1
	v_add_f32_dpp v38, v38, v38 quad_perm:[1,0,3,2] row_mask:0xf bank_mask:0xf
	s_waitcnt lgkmcnt(0)
	s_nop 0
	s_nop 1
	v_add_f32_dpp v38, v38, v38 quad_perm:[2,3,0,1] row_mask:0xf bank_mask:0xf
	s_waitcnt lgkmcnt(0)
	s_nop 0
	s_nop 1
	v_add_f32_dpp v38, v38, v38 row_ror:4 row_mask:0xf bank_mask:0xf
	s_waitcnt lgkmcnt(0)
	s_nop 0
	s_nop 1
	v_add_f32_dpp v38, v38, v38 row_ror:8 row_mask:0xf bank_mask:0xf
	s_waitcnt lgkmcnt(0)
	s_nop 0
	ds_bpermute_b32 v39, v128, v38
	s_waitcnt lgkmcnt(0)
	v_add_f32_e32 v38, v38, v39
	ds_bpermute_b32 v39, v129, v38
	s_waitcnt lgkmcnt(0)
; DEVI uint32_t pk(float a, float b) { const hwf32x2 v = {a, b}; return __builtin_bit_cast(uint32_t, __builtin_convertvector(v, hwbf16x2)); }
; DEVI float fast_sigmoid(float x) { return __builtin_amdgcn_rcpf(1.f + __expf(-x)); }
; DEVI float wsum16(float v) {
;   v += __shfl_xor(v, 1); v += __shfl_xor(v, 2); v += __shfl_xor(v, 4); v += __shfl_xor(v, 8); return v;
; }
; DEVI float wsum64(float v) { v = wsum16(v); v += __shfl_xor(v, 16); v += __shfl_xor(v, 32); return v; }
; __device__ void phase_conv(const P& p, int vb, int nvb, char* smem) {
;     ...
; #pragma unroll 2
;     for (int q = 0; q < CT / 4; q++) {
;       const int tk = wave * (CT / 4) + q;
;       float v[8];
;       const float4 x0 = *(const float4*)(cv + tk * 512 + lane * 8), x1 = *(const float4*)(cv + tk * 512 + lane * 8 + 4);
;       v[0] = x0.x; v[1] = x0.y; v[2] = x0.z; v[3] = x0.w; v[4] = x1.x; v[5] = x1.y; v[6] = x1.z; v[7] = x1.w;
;       float s = 0.f;
; #pragma unroll
;       for (int e = 0; e < 8; e++) s += v[e];
;       const float mu = wsum64(s) * (1.f / 512.f);
;       float s2 = 0.f;
; #pragma unroll
;       for (int e = 0; e < 8; e++) { v[e] -= mu; s2 += v[e] * v[e]; }
;       const float rstd = rsqrtf(wsum64(s2) * (1.f / 512.f) + EPS);
;       float s3 = 0.f;
; #pragma unroll
;       for (int e = 0; e < 8; e++) {
;         const float y = v[e] * rstd * gln[e] + bln[e];
;         const float sl = y * fast_sigmoid(y);
;         v[e] = sl; s3 += sl * sl;
;       }
;       const float r2 = rsqrtf(wsum64(s3) * (1.f / 512.f) + EPS);
;       uint4 o = make_uint4(pk(v[0] * r2, v[1] * r2), pk(v[2] * r2, v[3] * r2), pk(v[4] * r2, v[5] * r2), pk(v[6] * r2, v[7] * r2));
;       *(uint4*)(mixed + (size_t)(b * TP + t0 + tk) * 1024 + 512 + lane * 8) = o;
;     }
	v_add_f32_e32 v38, v38, v39
	v_fmamk_f32 v38, v38, 0x3b000000, v130
	v_cmp_gt_f32_e32 vcc, s26, v38
	v_mul_f32_e32 v39, 0x4b800000, v38
	s_nop 0
	v_cndmask_b32_e32 v38, v38, v39, vcc
	v_rsq_f32_e32 v38, v38
	s_nop 0
	v_mul_f32_e32 v39, 0x45800000, v38
	v_cndmask_b32_e32 v38, v38, v39, vcc
	v_pk_mul_f32 v[34:35], v[34:35], v[38:39] op_sel_hi:[1,0]
	s_nop 0
	v_pk_fma_f32 v[34:35], v[4:5], v[34:35], v[12:13]
	s_nop 0
	v_mul_f32_e32 v39, 0xbfb8aa3b, v34
	v_exp_f32_e32 v39, v39
	s_nop 0
	v_add_f32_e32 v39, 1.0, v39
	v_rcp_f32_e32 v40, v39
	v_mul_f32_e32 v39, 0xbfb8aa3b, v35
	v_exp_f32_e32 v39, v39
	s_nop 0
	v_add_f32_e32 v39, 1.0, v39
	v_pk_mul_f32 v[36:37], v[36:37], v[38:39] op_sel_hi:[1,0]
	v_rcp_f32_e32 v41, v39
	v_pk_fma_f32 v[36:37], v[6:7], v[36:37], v[14:15]
	v_pk_mul_f32 v[34:35], v[34:35], v[40:41]
	v_mul_f32_e32 v39, 0xbfb8aa3b, v36
	v_exp_f32_e32 v39, v39
	v_pk_mul_f32 v[40:41], v[34:35], v[34:35]
	v_add_f32_e32 v39, 1.0, v39
	v_rcp_f32_e32 v42, v39
	v_mul_f32_e32 v39, 0xbfb8aa3b, v37
	v_exp_f32_e32 v39, v39
	v_add_f32_e32 v40, v40, v41
	v_add_f32_e32 v39, 1.0, v39
	v_pk_mul_f32 v[16:17], v[16:17], v[38:39] op_sel_hi:[1,0]
	v_rcp_f32_e32 v43, v39
	v_pk_fma_f32 v[16:17], v[0:1], v[16:17], v[8:9]
	v_pk_mul_f32 v[36:37], v[36:37], v[42:43]
	v_mul_f32_e32 v39, 0xbfb8aa3b, v16
	v_exp_f32_e32 v39, v39
	v_pk_mul_f32 v[42:43], v[36:37], v[36:37]
	v_add_f32_e32 v39, 1.0, v39
	v_rcp_f32_e32 v44, v39
	v_mul_f32_e32 v39, 0xbfb8aa3b, v17
	v_exp_f32_e32 v39, v39
	v_add_f32_e32 v40, v42, v40
	v_add_f32_e32 v40, v43, v40
	v_add_f32_e32 v39, 1.0, v39
	v_pk_mul_f32 v[18:19], v[18:19], v[38:39] op_sel_hi:[1,0]
	v_rcp_f32_e32 v45, v39
	v_pk_fma_f32 v[18:19], v[2:3], v[18:19], v[10:11]
	v_pk_mul_f32 v[44:45], v[16:17], v[44:45]
	v_mul_f32_e32 v38, 0xbfb8aa3b, v18
	v_mul_f32_e32 v39, 0xbfb8aa3b, v19
	v_exp_f32_e32 v38, v38
	v_exp_f32_e32 v39, v39
	v_pk_mul_f32 v[16:17], v[44:45], v[44:45]
	v_add_f32_e32 v38, 1.0, v38
	v_add_f32_e32 v39, 1.0, v39
	v_rcp_f32_e32 v38, v38
	v_rcp_f32_e32 v39, v39
	v_add_f32_e32 v16, v16, v40
	v_add_f32_e32 v16, v17, v16
	v_pk_mul_f32 v[38:39], v[18:19], v[38:39]
	s_nop 0
	v_pk_mul_f32 v[18:19], v[38:39], v[38:39]
	s_nop 0
	v_add_f32_e32 v16, v18, v16
	v_add_f32_e32 v16, v19, v16
	s_nop 1
	v_add_f32_dpp v16, v16, v16 quad_perm:[1,0,3,2] row_mask:0xf bank_mask:0xf
	s_waitcnt lgkmcnt(0)
	s_nop 0
	s_nop 1
	v_add_f32_dpp v16, v16, v16 quad_perm:[2,3,0,1] row_mask:0xf bank_mask:0xf
	s_waitcnt lgkmcnt(0)
	s_nop 0
	s_nop 1
	v_add_f32_dpp v16, v16, v16 row_ror:4 row_mask:0xf bank_mask:0xf
	s_waitcnt lgkmcnt(0)
	s_nop 0
	s_nop 1
	v_add_f32_dpp v16, v16, v16 row_ror:8 row_mask:0xf bank_mask:0xf
	s_waitcnt lgkmcnt(0)
	s_nop 0
	ds_bpermute_b32 v17, v128, v16
	s_waitcnt lgkmcnt(0)
	v_add_f32_e32 v16, v16, v17
	ds_bpermute_b32 v17, v129, v16
	s_waitcnt lgkmcnt(0)
	v_add_f32_e32 v16, v16, v17
	v_fmamk_f32 v16, v16, 0x3b000000, v130
	v_cmp_gt_f32_e32 vcc, s26, v16
	v_mul_f32_e32 v17, 0x4b800000, v16
	s_nop 0
	v_cndmask_b32_e32 v16, v16, v17, vcc
	v_rsq_f32_e32 v16, v16
	s_nop 0
	v_mul_f32_e32 v17, 0x45800000, v16
	v_cndmask_b32_e32 v40, v16, v17, vcc
	v_pk_mul_f32 v[16:17], v[34:35], v[40:41] op_sel_hi:[1,0]
	v_pk_mul_f32 v[18:19], v[36:37], v[40:41] op_sel_hi:[1,0]
	v_cvt_pk_bf16_f32 v16, v16, v17
	v_cvt_pk_bf16_f32 v17, v18, v19
	v_pk_mul_f32 v[18:19], v[44:45], v[40:41] op_sel_hi:[1,0]
	v_pk_mul_f32 v[34:35], v[38:39], v[40:41] op_sel_hi:[1,0]
	v_cvt_pk_bf16_f32 v18, v18, v19
	v_cvt_pk_bf16_f32 v19, v34, v35
	v_add_u32_e32 v34, 23, v46
	v_ashrrev_i32_e32 v35, 31, v34
	v_lshlrev_b64 v[34:35], 11, v[34:35]
	v_lshl_add_u64 v[34:35], s[80:81], 0, v[34:35]
	v_lshl_add_u64 v[34:35], v[34:35], 0, v[22:23]
	v_add_co_u32_e32 v34, vcc, 0x2864000, v34
	s_nop 1
	v_addc_co_u32_e32 v35, vcc, 0, v35, vcc
	global_store_dwordx4 v[34:35], v[16:19], off offset:1024
	s_cbranch_scc0 .LBB0_137
	s_add_i32 s27, s27, s82
	s_add_i32 s0, s0, s1
	s_cmpk_gt_i32 s27, 0x557
	v_add_u32_e32 v30, s1, v30
	s_cbranch_scc0 .LBB0_134
	v_readlane_b32 s64, v248, 56
	v_readlane_b32 s65, v248, 57
